# v049 + hand-written P1 weight-transpose section: all 32 row loads per item in flight, ssd_norm_g scale applied in the transposed phase from one 32B read per lane
# speedup vs baseline: 1.0218x; 1.0134x over previous
.LBB0_61:
	s_cmpk_gt_i32 s2, 0xcff
	s_barrier
	s_cbranch_scc1 .LBB0_104
	s_waitcnt vmcnt(0)
	s_sub_u32 s12, s84, 0xf0
	s_subb_u32 s13, s85, 0
	s_load_dwordx2 s[14:15], s[12:13], 0x58
	s_load_dwordx4 s[20:23], s[12:13], 0xc0
	s_load_dwordx2 s[26:27], s[12:13], 0xe0
	v_mbcnt_hi_u32_b32 v0, -1, v194
	v_and_b32_e32 v1, 31, v0
	v_lshrrev_b32_e32 v2, 5, v0
	s_lshr_b32 s28, s86, 6
	s_mul_i32 s28, s28, 0x2100
	v_mul_u32_u24_e32 v3, 33, v2
	v_add_u32_e32 v3, v3, v1
	v_lshl_add_u32 v3, v3, 2, s28
	v_and_b32_e32 v5, 7, v0
	v_lshrrev_b32_e32 v6, 3, v0
	v_mul_u32_u24_e32 v4, 0x108, v5
	v_add_u32_e32 v4, v4, v6
	v_lshl_add_u32 v4, v4, 2, s28
	v_lshlrev_b32_e32 v8, 2, v1
	v_lshlrev_b32_e32 v9, 5, v5
	v_lshlrev_b32_e32 v10, 4, v5
	s_waitcnt lgkmcnt(0)
.Ltr_loop:
	s_cmpk_lt_i32 s2, 0x900
	s_cbranch_scc0 .Ltr_wout
	s_mul_hi_u32 s29, s2, 0x38e38e39
	s_lshr_b32 s29, s29, 5
	s_mul_i32 s30, s29, 0x90
	s_sub_i32 s30, s2, s30
	s_mul_i32 s31, s29, 0x121000
	s_lshl_b32 s36, s30, 7
	s_add_u32 s31, s31, s36
	s_add_u32 s34, s14, s31
	s_addc_u32 s35, s15, 0
	s_movk_i32 s36, 0x4840
	s_lshl_b32 s37, s30, 16
	s_lshl_b32 s38, s29, 7
	s_add_u32 s37, s37, s38
	s_add_u32 s37, s37, 0x8200000
	s_add_u32 s38, s26, s37
	s_addc_u32 s39, s27, 0
	s_movk_i32 s42, 0x800
	s_mov_b32 s43, 0
	s_branch .Ltr_item
.Ltr_wout:
	s_add_i32 s30, s2, 0xfffff700
	s_lshr_b32 s29, s30, 5
	s_and_b32 s30, s30, 31
	s_lshl_b32 s31, s29, 18
	s_lshl_b32 s36, s30, 7
	s_add_u32 s31, s31, s36
	s_add_u32 s34, s22, s31
	s_addc_u32 s35, s23, 0
	s_movk_i32 s36, 0x1000
	s_lshl_b32 s37, s30, 17
	s_lshl_b32 s38, s29, 7
	s_add_u32 s37, s37, s38
	s_add_u32 s37, s37, 0x8b80000
	s_add_u32 s38, s26, s37
	s_addc_u32 s39, s27, 0
	s_movk_i32 s42, 0x1000
	s_cmp_gt_u32 s29, 15
	s_cselect_b32 s43, 1, 0
	s_lshl_b32 s44, s29, 8
	s_add_i32 s44, s44, 0xfffff000
	s_ashr_i32 s45, s44, 31
	s_add_u32 s44, s20, s44
	s_addc_u32 s45, s21, s45
.Ltr_item:
	v_mad_u32_u24 v7, v2, s36, v8
	s_lshl_b32 s36, s36, 1
	v_mad_u32_u24 v12, v6, s42, v10
	s_cmp_eq_u32 s43, 0
	s_cbranch_scc1 .Ltr_nosc
	global_load_dwordx4 v[48:51], v9, s[44:45]
	global_load_dwordx4 v[52:55], v9, s[44:45] offset:16
.Ltr_nosc:
	global_load_dword v16, v7, s[34:35]
	s_add_u32 s34, s34, s36
	s_addc_u32 s35, s35, 0
	global_load_dword v17, v7, s[34:35]
	s_add_u32 s34, s34, s36
	s_addc_u32 s35, s35, 0
	global_load_dword v18, v7, s[34:35]
	s_add_u32 s34, s34, s36
	s_addc_u32 s35, s35, 0
	global_load_dword v19, v7, s[34:35]
	s_add_u32 s34, s34, s36
	s_addc_u32 s35, s35, 0
	global_load_dword v20, v7, s[34:35]
	s_add_u32 s34, s34, s36
	s_addc_u32 s35, s35, 0
	global_load_dword v21, v7, s[34:35]
	s_add_u32 s34, s34, s36
	s_addc_u32 s35, s35, 0
	global_load_dword v22, v7, s[34:35]
	s_add_u32 s34, s34, s36
	s_addc_u32 s35, s35, 0
	global_load_dword v23, v7, s[34:35]
	s_add_u32 s34, s34, s36
	s_addc_u32 s35, s35, 0
	global_load_dword v24, v7, s[34:35]
	s_add_u32 s34, s34, s36
	s_addc_u32 s35, s35, 0
	global_load_dword v25, v7, s[34:35]
	s_add_u32 s34, s34, s36
	s_addc_u32 s35, s35, 0
	global_load_dword v26, v7, s[34:35]
	s_add_u32 s34, s34, s36
	s_addc_u32 s35, s35, 0
	global_load_dword v27, v7, s[34:35]
	s_add_u32 s34, s34, s36
	s_addc_u32 s35, s35, 0
	global_load_dword v28, v7, s[34:35]
	s_add_u32 s34, s34, s36
	s_addc_u32 s35, s35, 0
	global_load_dword v29, v7, s[34:35]
	s_add_u32 s34, s34, s36
	s_addc_u32 s35, s35, 0
	global_load_dword v30, v7, s[34:35]
	s_add_u32 s34, s34, s36
	s_addc_u32 s35, s35, 0
	global_load_dword v31, v7, s[34:35]
	s_add_u32 s34, s34, s36
	s_addc_u32 s35, s35, 0
	global_load_dword v32, v7, s[34:35]
	s_add_u32 s34, s34, s36
	s_addc_u32 s35, s35, 0
	global_load_dword v33, v7, s[34:35]
	s_add_u32 s34, s34, s36
	s_addc_u32 s35, s35, 0
	global_load_dword v34, v7, s[34:35]
	s_add_u32 s34, s34, s36
	s_addc_u32 s35, s35, 0
	global_load_dword v35, v7, s[34:35]
	s_add_u32 s34, s34, s36
	s_addc_u32 s35, s35, 0
	global_load_dword v36, v7, s[34:35]
	s_add_u32 s34, s34, s36
	s_addc_u32 s35, s35, 0
	global_load_dword v37, v7, s[34:35]
	s_add_u32 s34, s34, s36
	s_addc_u32 s35, s35, 0
	global_load_dword v38, v7, s[34:35]
	s_add_u32 s34, s34, s36
	s_addc_u32 s35, s35, 0
	global_load_dword v39, v7, s[34:35]
	s_add_u32 s34, s34, s36
	s_addc_u32 s35, s35, 0
	global_load_dword v40, v7, s[34:35]
	s_add_u32 s34, s34, s36
	s_addc_u32 s35, s35, 0
	global_load_dword v41, v7, s[34:35]
	s_add_u32 s34, s34, s36
	s_addc_u32 s35, s35, 0
	global_load_dword v42, v7, s[34:35]
	s_add_u32 s34, s34, s36
	s_addc_u32 s35, s35, 0
	global_load_dword v43, v7, s[34:35]
	s_add_u32 s34, s34, s36
	s_addc_u32 s35, s35, 0
	global_load_dword v44, v7, s[34:35]
	s_add_u32 s34, s34, s36
	s_addc_u32 s35, s35, 0
	global_load_dword v45, v7, s[34:35]
	s_add_u32 s34, s34, s36
	s_addc_u32 s35, s35, 0
	global_load_dword v46, v7, s[34:35]
	s_add_u32 s34, s34, s36
	s_addc_u32 s35, s35, 0
	global_load_dword v47, v7, s[34:35]
	s_add_u32 s34, s34, s36
	s_addc_u32 s35, s35, 0
	s_waitcnt vmcnt(0)
	ds_write_b32 v3, v16
	ds_write_b32 v3, v17 offset:264
	ds_write_b32 v3, v18 offset:528
	ds_write_b32 v3, v19 offset:792
	ds_write_b32 v3, v20 offset:1056
	ds_write_b32 v3, v21 offset:1320
	ds_write_b32 v3, v22 offset:1584
	ds_write_b32 v3, v23 offset:1848
	ds_write_b32 v3, v24 offset:2112
	ds_write_b32 v3, v25 offset:2376
	ds_write_b32 v3, v26 offset:2640
	ds_write_b32 v3, v27 offset:2904
	ds_write_b32 v3, v28 offset:3168
	ds_write_b32 v3, v29 offset:3432
	ds_write_b32 v3, v30 offset:3696
	ds_write_b32 v3, v31 offset:3960
	ds_write_b32 v3, v32 offset:4224
	ds_write_b32 v3, v33 offset:4488
	ds_write_b32 v3, v34 offset:4752
	ds_write_b32 v3, v35 offset:5016
	ds_write_b32 v3, v36 offset:5280
	ds_write_b32 v3, v37 offset:5544
	ds_write_b32 v3, v38 offset:5808
	ds_write_b32 v3, v39 offset:6072
	ds_write_b32 v3, v40 offset:6336
	ds_write_b32 v3, v41 offset:6600
	ds_write_b32 v3, v42 offset:6864
	ds_write_b32 v3, v43 offset:7128
	ds_write_b32 v3, v44 offset:7392
	ds_write_b32 v3, v45 offset:7656
	ds_write_b32 v3, v46 offset:7920
	ds_write_b32 v3, v47 offset:8184
	s_waitcnt lgkmcnt(0)
	s_lshl_b32 s42, s42, 3
	ds_read2_b32 v[56:57], v4 offset0:0 offset1:33
	ds_read2_b32 v[58:59], v4 offset0:66 offset1:99
	ds_read2_b32 v[60:61], v4 offset0:132 offset1:165
	ds_read2_b32 v[62:63], v4 offset0:198 offset1:231
	s_waitcnt lgkmcnt(0)
	s_cmp_eq_u32 s43, 0
	s_cbranch_scc1 .Ltr_ns0
	v_mul_f32_e32 v56, v56, v48
	v_mul_f32_e32 v57, v57, v49
	v_mul_f32_e32 v58, v58, v50
	v_mul_f32_e32 v59, v59, v51
	v_mul_f32_e32 v60, v60, v52
	v_mul_f32_e32 v61, v61, v53
	v_mul_f32_e32 v62, v62, v54
	v_mul_f32_e32 v63, v63, v55
.Ltr_ns0:
	v_cvt_pk_bf16_f32 v44, v56, v57
	v_cvt_pk_bf16_f32 v45, v58, v59
	v_cvt_pk_bf16_f32 v46, v60, v61
	v_cvt_pk_bf16_f32 v47, v62, v63
	global_store_dwordx4 v12, v[44:47], s[38:39]
	s_add_u32 s38, s38, s42
	s_addc_u32 s39, s39, 0
	ds_read2_b32 v[56:57], v4 offset0:8 offset1:41
	ds_read2_b32 v[58:59], v4 offset0:74 offset1:107
	ds_read2_b32 v[60:61], v4 offset0:140 offset1:173
	ds_read2_b32 v[62:63], v4 offset0:206 offset1:239
	s_waitcnt lgkmcnt(0)
	s_cmp_eq_u32 s43, 0
	s_cbranch_scc1 .Ltr_ns1
	v_mul_f32_e32 v56, v56, v48
	v_mul_f32_e32 v57, v57, v49
	v_mul_f32_e32 v58, v58, v50
	v_mul_f32_e32 v59, v59, v51
	v_mul_f32_e32 v60, v60, v52
	v_mul_f32_e32 v61, v61, v53
	v_mul_f32_e32 v62, v62, v54
	v_mul_f32_e32 v63, v63, v55
.Ltr_ns1:
	v_cvt_pk_bf16_f32 v44, v56, v57
	v_cvt_pk_bf16_f32 v45, v58, v59
	v_cvt_pk_bf16_f32 v46, v60, v61
	v_cvt_pk_bf16_f32 v47, v62, v63
	global_store_dwordx4 v12, v[44:47], s[38:39]
	s_add_u32 s38, s38, s42
	s_addc_u32 s39, s39, 0
	ds_read2_b32 v[56:57], v4 offset0:16 offset1:49
	ds_read2_b32 v[58:59], v4 offset0:82 offset1:115
	ds_read2_b32 v[60:61], v4 offset0:148 offset1:181
	ds_read2_b32 v[62:63], v4 offset0:214 offset1:247
	s_waitcnt lgkmcnt(0)
	s_cmp_eq_u32 s43, 0
	s_cbranch_scc1 .Ltr_ns2
	v_mul_f32_e32 v56, v56, v48
	v_mul_f32_e32 v57, v57, v49
	v_mul_f32_e32 v58, v58, v50
	v_mul_f32_e32 v59, v59, v51
	v_mul_f32_e32 v60, v60, v52
	v_mul_f32_e32 v61, v61, v53
	v_mul_f32_e32 v62, v62, v54
	v_mul_f32_e32 v63, v63, v55
.Ltr_ns2:
	v_cvt_pk_bf16_f32 v44, v56, v57
	v_cvt_pk_bf16_f32 v45, v58, v59
	v_cvt_pk_bf16_f32 v46, v60, v61
	v_cvt_pk_bf16_f32 v47, v62, v63
	global_store_dwordx4 v12, v[44:47], s[38:39]
	s_add_u32 s38, s38, s42
	s_addc_u32 s39, s39, 0
	ds_read2_b32 v[56:57], v4 offset0:24 offset1:57
	ds_read2_b32 v[58:59], v4 offset0:90 offset1:123
	ds_read2_b32 v[60:61], v4 offset0:156 offset1:189
	ds_read2_b32 v[62:63], v4 offset0:222 offset1:255
	s_waitcnt lgkmcnt(0)
	s_cmp_eq_u32 s43, 0
	s_cbranch_scc1 .Ltr_ns3
	v_mul_f32_e32 v56, v56, v48
	v_mul_f32_e32 v57, v57, v49
	v_mul_f32_e32 v58, v58, v50
	v_mul_f32_e32 v59, v59, v51
	v_mul_f32_e32 v60, v60, v52
	v_mul_f32_e32 v61, v61, v53
	v_mul_f32_e32 v62, v62, v54
	v_mul_f32_e32 v63, v63, v55
.Ltr_ns3:
	v_cvt_pk_bf16_f32 v44, v56, v57
	v_cvt_pk_bf16_f32 v45, v58, v59
	v_cvt_pk_bf16_f32 v46, v60, v61
	v_cvt_pk_bf16_f32 v47, v62, v63
	global_store_dwordx4 v12, v[44:47], s[38:39]
	s_add_u32 s38, s38, s42
	s_addc_u32 s39, s39, 0
	s_add_i32 s2, s2, s3
	s_cmpk_lt_i32 s2, 0xd00
	s_cbranch_scc1 .Ltr_loop
